# P3 prompt-tile-first + early decode units on workgroups 240-255 only
# baseline (speedup 1.0000x reference)
; __device__ __forceinline__ int fresh_lane() { int l; asm volatile("v_mbcnt_lo_u32_b32 %0, -1, 0\n\tv_mbcnt_hi_u32_b32 %0, -1, %0" : "=v"(l)); return l; }
; #define SEAM(k) do { if (IN(k) && IN((k) + 1)) xcd_barrier(bar, C.wave); } while (0)
; #define PH5 { phase_attention(P, C, (P.pad >> 8) & 3, P.li); }
; #define RUN(k, BODY) do { if (IN(k)) { unsigned char* ws = P.ws; LAUNDER_GPTR(ws); BODY } } while (0)
; __device__ __forceinline__ void phase_attention(const Params& P, const Ctx& C, int parts, int qset) {
;     ...
;     for (int i = 0; i < 8; ++i) { const int x = (x0 + i) & 7;
;         for (;;) {
;             __syncthreads();
;             if (C.wave == 0 && fresh_lane() == 0) *slot = __hip_atomic_fetch_add(qc + 64 * x, 1u, __ATOMIC_RELAXED, __HIP_MEMORY_SCOPE_AGENT);
;             __syncthreads();
;             const unsigned u = *slot;
;             if (u >= 128u) break;
;             const int us = __builtin_amdgcn_readfirstlane((int)u);
; __global__ void __launch_bounds__(NWAVES * 64, 2) fwd_kernel(Params P) {
;     ...
;     RUN(3, PH3); SEAM(3);
;     RUN(4, PH4);
;     RUN(5, PH5); SEAM(5);
.LBB0_1136:
	s_bitcmp1_b32 s101, 1
	s_cbranch_scc1 .Lmy_e7
	s_bitset1_b32 s101, 1
	s_cmpk_lg_i32 s68, 0x100
	s_cbranch_scc1 .Lmy_e7
	s_bitset1_b32 s101, 3
	v_readlane_b32 s99, v254, 10
	s_cmpk_lt_u32 s99, 240
	s_cbranch_scc1 .Lmy_e7
	s_and_b32 s100, s99, 31
	s_mul_i32 s100, s100, 4
	s_add_i32 s100, s100, 1
	s_bitset1_b32 s101, 0
	s_waitcnt vmcnt(0)
	s_barrier
	s_mov_b64 s[2:3], -1
	s_branch .LBB0_1192

; __device__ __forceinline__ void phase_attention(const Params& P, const Ctx& C, int parts, int qset) {
;     ...
;             if (pq >= 0) { if (parts & 1) { if (fixed_ok) attn_prompt_unit<true>(P, C, x, pq); else attn_prompt_unit<false>(P, C, x, pq); } }
;             else { if (parts & 2) attn_decode_unit(P, C, x * 64 + dq); }
.LBB0_1215:
	s_bitcmp1_b32 s101, 0
	s_cbranch_scc1 .Lmy_e8
	s_bitcmp1_b32 s101, 3
	s_cbranch_scc0 .Lmy_e8
	v_readlane_b32 s99, v254, 13
	s_add_i32 s99, s99, s4
	s_cmpk_lt_u32 s99, 480
	s_cbranch_scc1 .Lmy_e8
	s_bitcmp0_b32 s4, 0
	s_cbranch_scc1 .LBB0_1200
